# attention static priority polarity flipped: waves 0-3 get s_setprio 1
# baseline (speedup 1.0000x reference)
; DI unsigned cvtpk(float lo, float hi) { unsigned r; asm volatile("v_cvt_pk_bf16_f32 %0, %1, %2" : "=v"(r) : "v"(lo), "v"(hi)); return r; }
; DI int v_st(int k, int c) { const int kk = (k & ~0xC) | ((k & 4) << 1) | ((k & 8) >> 1); return ((kk >> 3) * 4 + (c >> 5)) * 512 + ((kk & 7) * 32 + (c & 31)) * 2; }
; DI int v_rd_base(int lane) { return ((lane & 3) << 3) | (((lane >> 2) & 3) << 6) | (((lane >> 4) & 1) << 5) | (((lane >> 5) & 1) << 8); }
; #define SLOAD(i, k0) do { sr_[i].vs0 = ld8(&Vh[(long)((k0) + sr) * LDK + sc]); sr_[i].vs1 = ld8(&Vh[(long)((k0) + 32 + sr) * LDK + sc]); \
;     sr_[i].ks0 = ld8(&Kh[(long)((k0) + sr) * LDK + sc]); sr_[i].ks1 = ld8(&Kh[(long)((k0) + 32 + sr) * LDK + sc]); } while (0)
; #define SWRITE(b, i) do { *(bf16x8*)((char*)V_lds + (b) * SHM_V + vst0) = sr_[i].vs0;          \
;     *(bf16x8*)((char*)V_lds + (b) * SHM_V + vst1) = sr_[i].vs1; int kc = sc * 2;               \
;     *(bf16x8*)((char*)K_lds + (b) * SHM_K + KSWZ(sr, kc)) = sr_[i].ks0;                       \
;     *(bf16x8*)((char*)K_lds + (b) * SHM_K + KSWZ(32 + sr, kc)) = sr_[i].ks1; } while (0)
; DI void attn_dense_body(const bf16_t* __restrict__ Qb, const bf16_t* __restrict__ Kh, const bf16_t* __restrict__ Vh, ...
;     ...
;     for (int d0 = 0; d0 < 8; ++d0) { u32x4 w = {cvtpk(xf[d0][0], xf[d0][1]), cvtpk(xf[d0][2], xf[d0][3]), cvtpk(xf[d0][4], xf[d0][5]), cvtpk(xf[d0][6], xf[d0][7])}; qr[d0] = *reinterpret_cast<bf16x8*>(&w); }
;   }
;   const int sr = tid >> 4, sc = (tid & 15) * 8, vst0 = v_st(sr, sc), vst1 = v_st(32 + sr, sc);
;   const int vb0 = (int)(uintptr_t)V_lds + v_rd_base(lane);
;   struct { bf16x8 vs0, vs1, ks0, ks1; } sr_[2];
;     ...
;   f32x16 pA0, pA1, pB0, pB1; float mnA, mnB, alA, alB; bf16x8 pa0, pa1, pa2, pa3; const int NT = seq / KVBLK;
;   constexpr int SE = 0, SO = 1;
;   SLOAD(SE, 0); asm volatile("s_waitcnt vmcnt(0)" ::: "memory"); SWRITE(0, SE); __syncthreads();
;   qkt(pA0, pA1, K_lds, qr, r32, hi); partialSM(pA0, pA1, m_reg, mnA, alA);
.LBB0_834:
	s_or_b32 s4, s0, s12
	s_mov_b32 s5, s1
	s_lshl_b64 s[10:11], s[4:5], 1
	v_ashrrev_i32_e32 v176, 4, v160
	s_add_u32 s4, s96, s10
	v_cvt_pk_bf16_f32 v116, v114, v113
	v_cvt_pk_bf16_f32 v117, v106, v105
	v_cvt_pk_bf16_f32 v118, v98, v55
	v_cvt_pk_bf16_f32 v119, v90, v65
	v_cvt_pk_bf16_f32 v124, v88, v67
	v_cvt_pk_bf16_f32 v125, v86, v73
	v_cvt_pk_bf16_f32 v126, v84, v79
	v_cvt_pk_bf16_f32 v127, v82, v81
	v_cvt_pk_bf16_f32 v120, v40, v41
	v_cvt_pk_bf16_f32 v121, v42, v43
	v_cvt_pk_bf16_f32 v122, v44, v45
	v_cvt_pk_bf16_f32 v123, v46, v47
	v_cvt_pk_bf16_f32 v112, v56, v57
	v_cvt_pk_bf16_f32 v113, v58, v59
	v_cvt_pk_bf16_f32 v114, v60, v61
	v_cvt_pk_bf16_f32 v115, v62, v63
	v_cvt_pk_bf16_f32 v108, v76, v77
	v_cvt_pk_bf16_f32 v109, v74, v75
	v_cvt_pk_bf16_f32 v110, v70, v71
	v_cvt_pk_bf16_f32 v111, v68, v69
	v_cvt_pk_bf16_f32 v104, v38, v39
	v_cvt_pk_bf16_f32 v105, v36, v37
	v_cvt_pk_bf16_f32 v106, v34, v35
	v_cvt_pk_bf16_f32 v107, v32, v33
	v_cvt_pk_bf16_f32 v100, v28, v29
	v_cvt_pk_bf16_f32 v101, v30, v31
	v_cvt_pk_bf16_f32 v102, v18, v19
	v_cvt_pk_bf16_f32 v103, v20, v21
	v_cvt_pk_bf16_f32 v96, v22, v23
	v_cvt_pk_bf16_f32 v97, v26, v27
	v_cvt_pk_bf16_f32 v98, v16, v17
	v_lshlrev_b32_e32 v16, 3, v160
	v_add_u32_e32 v184, 32, v176
	s_addc_u32 s5, s97, s11
	v_readlane_b32 s13, v254, 38
	v_and_b32_e32 v178, 0x78, v16
	v_ashrrev_i32_e32 v177, 31, v176
	v_ashrrev_i32_e32 v185, 31, v184
	s_add_u32 s10, s13, s10
	v_readlane_b32 s13, v254, 39
	v_lshlrev_b32_e32 v72, 1, v178
	v_lshlrev_b64 v[48:49], 9, v[176:177]
	v_lshlrev_b64 v[12:13], 9, v[184:185]
	s_addc_u32 s11, s13, s11
	v_or_b32_e32 v8, v48, v72
	v_mov_b32_e32 v9, v49
	v_or_b32_e32 v12, v12, v72
	v_lshl_add_u64 v[0:1], s[10:11], 0, v[8:9]
	v_lshl_add_u64 v[4:5], s[10:11], 0, v[12:13]
	v_cvt_pk_bf16_f32 v99, v24, v25
	global_load_dwordx4 v[0:3], v[0:1], off
	s_nop 0
	global_load_dwordx4 v[4:7], v[4:5], off
	v_lshl_add_u64 v[8:9], s[4:5], 0, v[8:9]
	global_load_dwordx4 v[8:11], v[8:9], off
	v_lshl_add_u64 v[12:13], s[4:5], 0, v[12:13]
	global_load_dwordx4 v[12:15], v[12:13], off
	v_and_b32_e32 v18, 0xfffff0, v176
	v_lshlrev_b32_e32 v19, 1, v176
	v_lshrrev_b32_e32 v20, 1, v176
	v_and_b32_e32 v21, 3, v176
	v_and_or_b32 v18, v19, 8, v18
	v_and_or_b32 v19, v20, 4, v21
	v_and_b32_e32 v20, 0xfffff0, v184
	v_lshlrev_b32_e32 v21, 1, v184
	v_bfe_u32 v16, v16, 5, 2
	v_lshrrev_b32_e32 v18, 1, v18
	v_and_or_b32 v20, v21, 8, v20
	v_or_b32_e32 v18, v18, v16
	v_lshrrev_b32_e32 v20, 1, v20
	v_lshlrev_b32_e32 v19, 6, v19
	v_and_b32_e32 v23, 48, v72
	v_lshlrev_b32_e32 v18, 9, v18
	v_or_b32_e32 v16, v20, v16
	v_and_b32_e32 v17, 0x70, v160
	v_lshlrev_b32_e32 v22, 8, v176
	v_or3_b32 v18, v18, v19, v23
	v_lshlrev_b32_e32 v16, 9, v16
	v_bitop3_b32 v21, v72, v22, v17 bitop3:0xde
	v_or3_b32 v16, v16, v19, v23
	v_add_u32_e32 v204, 0, v18
	v_add_u32_e32 v203, 0, v21
	s_waitcnt vmcnt(0)
	v_add_u32_e32 v205, 0, v16
	s_waitcnt vmcnt(3)
	ds_write_b128 v204, v[0:3]
	s_waitcnt vmcnt(2)
	ds_write_b128 v205, v[4:7]
	s_waitcnt vmcnt(1)
	ds_write_b128 v203, v[8:11] offset:32768
	v_lshlrev_b32_e32 v0, 8, v184
	v_bitop3_b32 v0, v72, v0, v17 bitop3:0xde
	v_add_u32_e32 v206, 0, v0
	v_lshlrev_b32_e32 v0, 4, v196
	v_lshlrev_b32_e32 v66, 8, v196
	v_and_b32_e32 v67, 0x70, v0
	v_bitop3_b32 v0, v180, v66, v67 bitop3:0xde
	v_add_u32_e32 v207, 0, v0
	s_waitcnt vmcnt(0)
	ds_write_b128 v206, v[12:15] offset:32768
	s_waitcnt lgkmcnt(0)
	s_barrier
	ds_read_b128 v[0:3], v207 offset:32768
	ds_read_b128 v[4:7], v207 offset:40960
	s_waitcnt lgkmcnt(1)
	v_mfma_f32_32x32x16_bf16 v[16:31], v[0:3], v[116:119], 0
	v_or_b32_e32 v0, 32, v180
	v_bitop3_b32 v0, v0, v66, v67 bitop3:0xde
	v_add_u32_e32 v210, 0, v0
	s_add_i32 s13, 0, 0x10000
	v_and_b32_e32 v74, 63, v160
	v_lshlrev_b32_e32 v68, 3, v74
	v_add_u32_e32 v186, 64, v176
	s_waitcnt lgkmcnt(0)
	v_mfma_f32_32x32x16_bf16 v[32:47], v[4:7], v[116:119], 0
	ds_read_b128 v[0:3], v210 offset:32768
	ds_read_b128 v[4:7], v210 offset:40960
	v_ashrrev_i32_e32 v187, 31, v186
	v_add_u32_e32 v188, 0x60, v176
	v_lshlrev_b64 v[8:9], 9, v[186:187]
	v_ashrrev_i32_e32 v189, 31, v188
	v_lshlrev_b32_e32 v70, 1, v74
	v_or_b32_e32 v8, v8, v72
	s_waitcnt lgkmcnt(1)
	v_mfma_f32_32x32x16_bf16 v[16:31], v[0:3], v[124:127], v[16:31]
	v_or_b32_e32 v0, 64, v180
	v_bitop3_b32 v0, v0, v66, v67 bitop3:0xde
	v_add_u32_e32 v211, 0, v0
	v_lshlrev_b64 v[12:13], 9, v[188:189]
	v_lshl_add_u64 v[10:11], s[10:11], 0, v[8:9]
	v_or_b32_e32 v12, v12, v72
	v_lshl_add_u64 v[8:9], s[4:5], 0, v[8:9]
	s_waitcnt lgkmcnt(0)
	v_mfma_f32_32x32x16_bf16 v[32:47], v[4:7], v[124:127], v[32:47]
	ds_read_b128 v[0:3], v211 offset:32768
	ds_read_b128 v[4:7], v211 offset:40960
	v_lshl_add_u64 v[14:15], s[10:11], 0, v[12:13]
	v_add_u32_e32 v190, 0x80, v176
	v_ashrrev_i32_e32 v191, 31, v190
	v_add_u32_e32 v192, 0xa0, v176
	v_ashrrev_i32_e32 v193, 31, v192
	s_cmp_lg_u32 0, -1
	s_waitcnt lgkmcnt(1)
	v_mfma_f32_32x32x16_bf16 v[16:31], v[0:3], v[120:123], v[16:31]
	v_or_b32_e32 v0, 0x60, v180
	v_bitop3_b32 v0, v0, v66, v67 bitop3:0xde
	v_add_u32_e32 v208, 0, v0
	s_mov_b32 s69, s68
	s_mov_b32 s70, s68
	s_mov_b32 s71, s68
	s_mov_b32 s72, s68
	s_waitcnt lgkmcnt(0)
	v_mfma_f32_32x32x16_bf16 v[32:47], v[4:7], v[120:123], v[32:47]
	ds_read_b128 v[0:3], v208 offset:32768
	ds_read_b128 v[4:7], v208 offset:40960
	s_mov_b32 s73, s68
	s_mov_b32 s74, s68
	s_mov_b32 s75, s68
	s_mov_b32 s76, s68
	s_mov_b32 s77, s68
	s_mov_b32 s78, s68
	s_waitcnt lgkmcnt(1)
	v_mfma_f32_32x32x16_bf16 v[16:31], v[0:3], v[112:115], v[16:31]
	v_or_b32_e32 v0, 0x80, v180
	v_bitop3_b32 v0, v0, v66, v67 bitop3:0xde
	v_add_u32_e32 v209, 0, v0
	ds_read_b128 v[0:3], v209 offset:32768
	s_mov_b32 s79, s68
	s_mov_b32 s80, s68
	s_mov_b32 s81, s68
	s_waitcnt lgkmcnt(1)
; #define SLOAD(i, k0) do { sr_[i].vs0 = ld8(&Vh[(long)((k0) + sr) * LDK + sc]); sr_[i].vs1 = ld8(&Vh[(long)((k0) + 32 + sr) * LDK + sc]); \
;     sr_[i].ks0 = ld8(&Kh[(long)((k0) + sr) * LDK + sc]); sr_[i].ks1 = ld8(&Kh[(long)((k0) + 32 + sr) * LDK + sc]); } while (0)
; #define SWRITE(b, i) do { *(bf16x8*)((char*)V_lds + (b) * SHM_V + vst0) = sr_[i].vs0;          \
;     *(bf16x8*)((char*)V_lds + (b) * SHM_V + vst1) = sr_[i].vs1; int kc = sc * 2;               \
;     *(bf16x8*)((char*)K_lds + (b) * SHM_K + KSWZ(sr, kc)) = sr_[i].ks0;                       \
;     *(bf16x8*)((char*)K_lds + (b) * SHM_K + KSWZ(32 + sr, kc)) = sr_[i].ks1; } while (0)
; #define SWAIT() asm volatile("s_waitcnt vmcnt(4)" ::: "memory")
; DI void partialSM(f32x16& p0, f32x16& p1, float& m_reg, float& mn, float& alpha) {
;   constexpr float C = SCALE * 1.4426950408889634f;
;   float pmax = p0[0]; for (int r = 1; r < 16; ++r) pmax = fmaxf(pmax, p0[r]); for (int r = 0; r < 16; ++r) pmax = fmaxf(pmax, p1[r]);
;   { auto rr = __builtin_amdgcn_permlane32_swap(__float_as_uint(pmax), __float_as_uint(pmax), false, false);
;     pmax = fmaxf(__uint_as_float(rr[0]), __uint_as_float(rr[1])); }
;   if (__builtin_expect(__all(pmax - m_reg <= THR / SCALE), 1)) { mn = m_reg; alpha = 1.f; }
;   else { mn = fmaxf(m_reg, pmax); alpha = __builtin_amdgcn_exp2f((m_reg - mn) * C); m_reg = mn; }
;   float mnC = -mn * C;
;   for (int r = 0; r < 16; ++r) p0[r] = fmaf(p0[r], C, mnC); for (int r = 0; r < 16; ++r) p1[r] = fmaf(p1[r], C, mnC);
;   for (int r = 0; r < 16; ++r) p0[r] = __builtin_amdgcn_exp2f(p0[r]);
; }
; DI void attn_dense_body(const bf16_t* __restrict__ Qb, const bf16_t* __restrict__ Kh, const bf16_t* __restrict__ Vh, ...
;     ...
;   f32x16 pA0, pA1, pB0, pB1; float mnA, mnB, alA, alB; bf16x8 pa0, pa1, pa2, pa3; const int NT = seq / KVBLK;
;   constexpr int SE = 0, SO = 1;
;   SLOAD(SE, 0); asm volatile("s_waitcnt vmcnt(0)" ::: "memory"); SWRITE(0, SE); __syncthreads();
;   qkt(pA0, pA1, K_lds, qr, r32, hi); partialSM(pA0, pA1, m_reg, mnA, alA);
;   SLOAD(SO, KVBLK); if (2 < NT) SLOAD(SE, 2 * KVBLK);
;   SWAIT(); SWRITE(1, SO); __syncthreads();
	v_mfma_f32_32x32x16_bf16 v[32:47], v[4:7], v[112:115], v[32:47]
	ds_read_b128 v[4:7], v209 offset:40960
	s_mov_b32 s82, s68
	s_mov_b32 s83, s68
	s_mov_b32 s16, 4
	v_mov_b32_e32 v200, 0
	s_waitcnt lgkmcnt(1)
	v_mfma_f32_32x32x16_bf16 v[16:31], v[0:3], v[108:111], v[16:31]
	v_and_b32_e32 v0, 0x3fffffc0, v160
	v_lshl_add_u32 v198, v0, 2, s13
	v_or_b32_e32 v0, 0xa0, v180
	v_bitop3_b32 v0, v0, v66, v67 bitop3:0xde
	v_add_u32_e32 v212, 0, v0
	ds_read_b128 v[0:3], v212 offset:32768
	s_cselect_b32 s13, 0, 0
	s_waitcnt lgkmcnt(1)
	v_mfma_f32_32x32x16_bf16 v[32:47], v[4:7], v[108:111], v[32:47]
	v_lshlrev_b32_e32 v4, 4, v74
	v_and_b32_e32 v4, 0xc0, v4
	v_and_or_b32 v69, v68, 24, v4
	ds_read_b128 v[4:7], v212 offset:40960
	v_lshl_add_u32 v199, v196, 2, v198
	s_waitcnt lgkmcnt(1)
	v_mfma_f32_32x32x16_bf16 v[16:31], v[0:3], v[104:107], v[16:31]
	v_or_b32_e32 v0, 0xc0, v180
	v_bitop3_b32 v0, v0, v66, v67 bitop3:0xde
	v_add_u32_e32 v213, 0, v0
	ds_read_b128 v[0:3], v213 offset:32768
	global_load_dwordx4 v[50:53], v[10:11], off
	global_load_dwordx4 v[54:57], v[14:15], off
	v_lshl_add_u64 v[10:11], s[4:5], 0, v[12:13]
	global_load_dwordx4 v[58:61], v[8:9], off
	global_load_dwordx4 v[62:65], v[10:11], off
	s_waitcnt lgkmcnt(0)
	v_mfma_f32_32x32x16_bf16 v[16:31], v[0:3], v[100:103], v[16:31]
	v_or_b32_e32 v0, 0xe0, v180
	v_bitop3_b32 v0, v0, v66, v67 bitop3:0xde
	v_add_u32_e32 v214, 0, v0
	ds_read_b128 v[0:3], v214 offset:32768
	v_mfma_f32_32x32x16_bf16 v[32:47], v[4:7], v[104:107], v[32:47]
	v_and_b32_e32 v4, 32, v70
	v_and_b32_e32 v5, 0x100, v68
	v_or3_b32 v75, v69, v4, v5
	ds_read_b128 v[4:7], v213 offset:40960
	ds_read_b128 v[66:69], v214 offset:40960
	v_lshlrev_b64 v[70:71], 9, v[192:193]
	v_or_b32_e32 v70, v70, v72
	s_waitcnt lgkmcnt(1)
	v_mfma_f32_32x32x16_bf16 v[32:47], v[4:7], v[100:103], v[32:47]
	v_add_u32_e32 v202, s13, v75
	v_mfma_f32_32x32x16_bf16 v[16:31], v[0:3], v[96:99], v[16:31]
	v_mov_b64_e32 v[0:1], s[68:69]
	v_mov_b64_e32 v[14:15], s[82:83]
	v_mov_b64_e32 v[2:3], s[70:71]
	v_mov_b64_e32 v[4:5], s[72:73]
	v_mov_b64_e32 v[6:7], s[74:75]
	v_mov_b64_e32 v[8:9], s[76:77]
	v_mov_b64_e32 v[10:11], s[78:79]
	s_waitcnt lgkmcnt(0)
	v_mfma_f32_32x32x16_bf16 v[32:47], v[66:69], v[96:99], v[32:47]
	s_nop 2
	v_max_f32_e32 v66, v17, v17
	v_max_f32_e32 v67, v16, v16
	v_max_f32_e32 v66, v67, v66
	v_max3_f32 v66, v66, v18, v19
	v_max3_f32 v66, v66, v20, v21
	v_max3_f32 v66, v66, v22, v23
	v_max3_f32 v66, v66, v24, v25
	v_max3_f32 v66, v66, v26, v27
	v_max3_f32 v66, v66, v28, v29
	v_max3_f32 v66, v66, v30, v31
	v_max3_f32 v66, v66, v32, v33
	v_max3_f32 v66, v66, v34, v35
	v_max3_f32 v66, v66, v36, v37
	v_max3_f32 v66, v66, v38, v39
	v_max3_f32 v66, v66, v40, v41
	v_max3_f32 v66, v66, v42, v43
	v_max3_f32 v66, v66, v44, v45
	v_max3_f32 v76, v66, v46, v47
	v_lshlrev_b64 v[66:67], 9, v[190:191]
	v_or_b32_e32 v66, v66, v72
	v_lshl_add_u64 v[68:69], s[10:11], 0, v[66:67]
	v_lshl_add_u64 v[66:67], s[4:5], 0, v[66:67]
	v_lshl_add_u64 v[72:73], s[10:11], 0, v[70:71]
	global_load_dwordx4 v[128:131], v[68:69], off
	global_load_dwordx4 v[136:139], v[72:73], off
	v_lshl_add_u64 v[68:69], s[4:5], 0, v[70:71]
	global_load_dwordx4 v[132:135], v[66:67], off
	global_load_dwordx4 v[140:143], v[68:69], off
	v_mov_b32_e32 v77, v76
	s_nop 1
	v_permlane32_swap_b32_e32 v76, v77
	v_max_f32_e32 v66, v77, v77
	v_max_f32_e32 v67, v76, v76
	v_max_f32_e32 v66, v67, v66
	s_waitcnt vmcnt(4)
	s_waitcnt vmcnt(7)
	ds_write_b128 v204, v[50:53] offset:16384
	s_waitcnt vmcnt(6)
	ds_write_b128 v205, v[54:57] offset:16384
	s_waitcnt vmcnt(5)
	ds_write_b128 v203, v[58:61] offset:49152
	s_waitcnt vmcnt(4)
	ds_write_b128 v206, v[62:65] offset:49152
	v_max_f32_e32 v50, 0xf149f2ca, v66
	v_sub_f32_e32 v51, 0xf149f2ca, v50
	v_mul_f32_e32 v51, 0x3e0293ee, v51
	v_add_f32_e32 v67, 0x7149f2ca, v66
	v_exp_f32_e32 v51, v51
	v_cmp_ge_f32_e32 vcc, s95, v67
	s_cmp_eq_u64 vcc, exec
	s_cselect_b64 vcc, -1, 0
	v_cndmask_b32_e64 v215, v51, 1.0, vcc
	v_mov_b32_e32 v51, 0xf149f2ca
	v_cndmask_b32_e32 v168, v50, v51, vcc
	v_mul_f32_e32 v50, 0xbe0293ee, v168
	v_fmamk_f32 v16, v16, 0x3e0293ee, v50
	v_exp_f32_e32 v161, v16
	v_fmamk_f32 v16, v17, 0x3e0293ee, v50
	v_exp_f32_e32 v175, v16
	v_fmamk_f32 v16, v18, 0x3e0293ee, v50
	v_exp_f32_e32 v162, v16
	v_fmamk_f32 v16, v19, 0x3e0293ee, v50
	v_exp_f32_e32 v219, v16
	v_fmamk_f32 v16, v20, 0x3e0293ee, v50
	v_exp_f32_e32 v174, v16
	v_fmamk_f32 v16, v21, 0x3e0293ee, v50
	v_exp_f32_e32 v222, v16
	v_fmamk_f32 v16, v22, 0x3e0293ee, v50
	v_exp_f32_e32 v163, v16
	v_fmamk_f32 v16, v23, 0x3e0293ee, v50
	v_exp_f32_e32 v173, v16
	v_fmamk_f32 v16, v24, 0x3e0293ee, v50
	v_exp_f32_e32 v164, v16
	v_fmamk_f32 v16, v25, 0x3e0293ee, v50
	v_exp_f32_e32 v171, v16
	v_fmamk_f32 v16, v26, 0x3e0293ee, v50
	v_exp_f32_e32 v165, v16
	v_fmamk_f32 v16, v27, 0x3e0293ee, v50
	s_addk_i32 s13, 0x4000
	v_exp_f32_e32 v172, v16
	v_fmamk_f32 v16, v28, 0x3e0293ee, v50
	s_add_u32 s0, s0, s12
	v_exp_f32_e32 v166, v16
	v_fmamk_f32 v16, v29, 0x3e0293ee, v50
	s_addc_u32 s1, s1, 0
	v_pk_fma_f32 v[144:145], v[46:47], s[42:43], v[50:51] op_sel_hi:[1,0,0]
	v_pk_fma_f32 v[150:151], v[44:45], s[42:43], v[50:51] op_sel_hi:[1,0,0]
	v_pk_fma_f32 v[154:155], v[42:43], s[42:43], v[50:51] op_sel_hi:[1,0,0]
	v_pk_fma_f32 v[146:147], v[40:41], s[42:43], v[50:51] op_sel_hi:[1,0,0]
	v_pk_fma_f32 v[148:149], v[38:39], s[42:43], v[50:51] op_sel_hi:[1,0,0]
	v_pk_fma_f32 v[152:153], v[36:37], s[42:43], v[50:51] op_sel_hi:[1,0,0]
	v_pk_fma_f32 v[156:157], v[34:35], s[42:43], v[50:51] op_sel_hi:[1,0,0]
	v_pk_fma_f32 v[158:159], v[32:33], s[42:43], v[50:51] op_sel_hi:[1,0,0]
	v_exp_f32_e32 v169, v16
	v_fmamk_f32 v16, v30, 0x3e0293ee, v50
	v_fmac_f32_e32 v50, 0x3e0293ee, v31
	s_lshl_b64 s[0:1], s[0:1], 1
	v_readlane_b32 s10, v255, 31
	v_exp_f32_e32 v167, v16
	v_exp_f32_e32 v170, v50
	v_and_b32_e32 v16, 15, v160
	s_add_u32 s0, s10, s0
	v_readlane_b32 s10, v255, 32
	v_lshl_or_b32 v48, v16, 4, v48
	s_addc_u32 s1, s10, s1
	v_mov_b64_e32 v[12:13], s[80:81]
	v_lshl_add_u64 v[194:195], s[0:1], 0, v[48:49]
	v_mov_b64_e32 v[62:63], v[14:15]
	v_mov_b64_e32 v[46:47], v[14:15]
	v_mov_b64_e32 v[30:31], v[14:15]
	v_cmp_gt_u32_e64 s[4:5], 32, v74
	v_add_u32_e32 v201, s13, v75
	v_mov_b64_e32 v[60:61], v[12:13]
	v_mov_b64_e32 v[58:59], v[10:11]
	v_mov_b64_e32 v[56:57], v[8:9]
	v_mov_b64_e32 v[54:55], v[6:7]
	v_mov_b64_e32 v[52:53], v[4:5]
	v_mov_b64_e32 v[50:51], v[2:3]
	v_mov_b64_e32 v[48:49], v[0:1]
	v_mov_b64_e32 v[44:45], v[12:13]
	v_mov_b64_e32 v[42:43], v[10:11]
	v_mov_b64_e32 v[40:41], v[8:9]
	v_mov_b64_e32 v[38:39], v[6:7]
	v_mov_b64_e32 v[36:37], v[4:5]
	v_mov_b64_e32 v[34:35], v[2:3]
	v_mov_b64_e32 v[32:33], v[0:1]
	v_mov_b64_e32 v[28:29], v[12:13]
	v_mov_b64_e32 v[26:27], v[10:11]
	v_mov_b64_e32 v[24:25], v[8:9]
	v_mov_b64_e32 v[22:23], v[6:7]
	v_mov_b64_e32 v[20:21], v[4:5]
	v_mov_b64_e32 v[18:19], v[2:3]
	v_mov_b64_e32 v[16:17], v[0:1]
	v_readfirstlane_b32 s100, v252
	s_nop 3
	s_lshr_b32 s100, s100, 6
	s_cmp_ge_u32 s100, 4
	s_cbranch_scc1 .Lattn_prio_done
	s_setprio 1
